# FFN-down conversion tail starts without waiting for the residual epilogue's store/atomic acknowledgements (counted wait for the trailing LDS-DMA only), on top of the conversion-loop prefetch fix
# baseline (speedup 1.0000x reference)
; __device__ __forceinline__ PItem p0_decode(const Args& a, int it) {
;     constexpr int I_IN = 16 * 96, I_OUT = 16 * 32, I_W1 = 16 * 88, I_W2 = 44 * 32, I_LAYER = I_IN + I_OUT + 2 * I_W1 + I_W2;
;     const int l = it / I_LAYER, e = l >> 1, odd = l & 1; int r = it % I_LAYER;
;     unsigned char* wl = a.ws + WS_W + (size_t)l * W_LAYER; float* cv = (float*)(a.ws + WS_CVEC) + (size_t)l * CVEC_LAYER;
;     PItem p;
;     if (r < I_IN) { const int kb = r / 96, nb = r % 96; p.W = (odd ? a.in[13] : a.in[5]) + (size_t)e * D * EIN; p.N = EIN; p.K = D; p.g = l > 0 ? a.in[21] + (size_t)(l - 1) * D : nullptr; p.be = l > 0 ? a.in[22] + (size_t)(l - 1) * D : nullptr;
;         p.WT = (bf16*)(wl + W_IN); p.drow0 = in_dst_row(32 * nb, odd); p.k0 = 64 * kb; p.n0 = 32 * nb; p.c1 = cv; p.c2 = cv + EIN; return p; } r -= I_IN;
;     if (r < I_OUT) { const int kb = r / 32, nb = r % 32; p.W = (odd ? a.in[15] : a.in[6]) + (size_t)e * D * D; p.N = D; p.K = D; p.g = nullptr; p.be = nullptr;
;         p.WT = (bf16*)(wl + W_OUT); p.drow0 = 32 * nb; p.k0 = 64 * kb; p.n0 = 32 * nb; p.c1 = nullptr; p.c2 = nullptr; return p; } r -= I_OUT;
;     if (r < 2 * I_W1) { const int second = r >= I_W1; if (second) r -= I_W1; const int kb = r / 88, nb = r % 88, n0 = 32 * nb; p.W = (second ? a.in[17] : a.in[16]) + (size_t)l * D * DFF; p.N = DFF; p.K = D;
;         p.g = a.in[19] + (size_t)l * D; p.be = a.in[20] + (size_t)l * D; p.WT = (bf16*)(wl + W_13); p.drow0 = 256 * (n0 >> 7) + (second ? 128 : 0) + (n0 & 127); p.k0 = 64 * kb; p.n0 = n0; p.c1 = cv + 2 * EIN; p.c2 = cv + 2 * EIN + NUP; return p; } r -= 2 * I_W1;
; __global__ void __launch_bounds__(NWAVES * 64, 2) mk_fwd(Args args) {
;     ...
;                   if (l < 3) { if (mfirst > 0) { if ((int)blockIdx.x < mfirst) { p_convert_tail(F, args, (l + 1) * P_ILAYER, (l + 2) * P_ILAYER - ((F.G == 256) ? (l == 0 ? 768 : 1792) : 0), (int)blockIdx.x, mfirst); if (l == 0) p_state_copies_tail(F, args, (int)blockIdx.x, mfirst); } }
;                   else { p_convert_tail(F, args, (l + 1) * P_ILAYER, (l + 2) * P_ILAYER - ((F.G == 256) ? (l == 0 ? 768 : 1792) : 0), (int)blockIdx.x, F.G); if (l == 0) p_state_copies_tail(F, args, (int)blockIdx.x, F.G); } } } }
.LBB0_1546:
	s_waitcnt vmcnt(24)
	s_barrier
	v_readlane_b32 s0, v255, 62
	s_cmp_lg_u32 s0, 3
	s_mov_b64 s[10:11], -1
	v_readlane_b32 s1, v255, 63
	s_cbranch_scc0 .LBB0_1764
	s_cmp_lt_i32 s29, 33
	s_cbranch_scc0 .LBB0_1627
	v_readlane_b32 s0, v255, 62
	v_readlane_b32 s1, v255, 63
	s_mul_i32 s2, s0, 0x1880
	v_readlane_b32 s0, v255, 53
	v_readlane_b32 s1, v255, 54
	s_and_b64 s[0:1], s[0:1], exec
	s_movk_i32 s0, 0xfd00
	s_cselect_b32 s7, s0, 0xfffff900
	v_readlane_b32 s0, v252, 62
	v_readlane_b32 s1, v252, 63
	s_and_b64 s[0:1], s[0:1], exec
	s_cselect_b32 s0, s7, 0
	s_add_i32 s7, s2, s0
	v_readlane_b32 s0, v253, 60
	s_addk_i32 s7, 0x3100
	v_mbcnt_lo_u32_b32 v0, -1, 0
	v_mbcnt_hi_u32_b32 v0, -1, v0
	s_add_i32 s29, s0, s2
	v_add_u32_e32 v0, s75, v0
	s_cmp_ge_i32 s29, s7
	s_cbranch_scc1 .LBB0_1601
	s_mul_hi_i32 s0, s29, 0x5397829d
	s_lshr_b32 s1, s0, 31
	s_ashr_i32 s0, s0, 11
	s_add_i32 s26, s0, s1
	s_mul_i32 s1, s26, 0x1880
	s_ashr_i32 s30, s26, 1
	s_and_b32 s0, s26, 1
	s_sub_i32 s1, s29, s1
	s_ashr_i32 s27, s26, 31
	s_mul_i32 s10, s26, 0x1880000
	v_readlane_b32 s11, v253, 5
	s_mul_hi_i32 s2, s26, 0x1880000
	s_add_u32 s22, s11, s10
	v_readlane_b32 s10, v253, 6
	s_addc_u32 s23, s10, s2
	s_mul_i32 s10, s26, 0x11000
	v_readlane_b32 s11, v253, 7
	s_mul_hi_i32 s2, s26, 0x11000
	s_add_u32 s24, s11, s10
	v_readlane_b32 s10, v253, 8
	s_addc_u32 s25, s10, s2
	s_cmpk_gt_i32 s1, 0x5ff
	s_mov_b64 s[46:47], -1
	s_cbranch_scc0 .LBB0_1558
	s_cmpk_gt_u32 s1, 0x7ff
	s_cbranch_scc0 .LBB0_1555
	s_mov_b64 s[18:19], -1
	s_cmpk_gt_u32 s1, 0x12ff
	s_mul_hi_i32 s2, s26, 0xb00000
	s_mul_i32 s13, s26, 0xb00000
	s_cbranch_scc0 .LBB0_1553
	v_readlane_b32 s56, v253, 26
	v_readlane_b32 s57, v253, 27
	s_add_u32 s10, s56, s13
	s_addc_u32 s11, s57, s2
	s_add_u32 s14, s22, 0x1300000
	s_addc_u32 s15, s23, 0
	s_lshl_b32 s16, s1, 1
	s_lshl_b32 s12, s1, 5
	s_and_b32 s16, s16, 0x7fffffc0
	v_readlane_b32 s58, v253, 28
	v_readlane_b32 s59, v253, 29
	v_readlane_b32 s60, v253, 30
	v_readlane_b32 s61, v253, 31
	v_readlane_b32 s62, v253, 32
	v_readlane_b32 s63, v253, 33
	s_and_b32 s12, s12, 0x3e0
	s_addk_i32 s16, 0xda00
	s_mov_b64 s[18:19], 0

; #define GAS __attribute__((address_space(1)))
; #define LAS __attribute__((address_space(3)))
; __device__ __forceinline__ void p0_item_load(const PItem& it, int lane, f32x4 (&v)[8]) {
; #pragma unroll
;     for (int i = 0; i < 8; ++i) v[i] = __builtin_nontemporal_load((const GAS f32x4*)(it.W + (size_t)(it.k0 + 8 * i + (lane >> 3)) * it.N + it.n0 + 4 * (lane & 7)));
; }
; __device__ __forceinline__ void p0_item_process(const PItem& it, int lane, const f32x4 (&v)[8], LAS float* scr) {
;     LAS float* gl = scr + 64 * 36 + 32; LAS float* bl = gl + 64;
;     ...
; #pragma unroll
;     for (int i = 0; i < 8; ++i) *(LAS f32x4*)(scr + SCR_ROW(8 * i + (lane >> 3)) + 4 * (lane & 7)) = v[i];
; __device__ __forceinline__ void p0_convert(const Frame& F, const Args& a, int it_lo, int it_hi, int widx, int nw, LAS float* scr) {
;     ...
;         PItem cur = p0_decode(a, it0); f32x4 vc[8]; p0_item_load(cur, F.lane, vc);
.LBB0_1565:
	v_bfe_u32 v70, v0, 3, 3
	v_or_b32_e32 v71, 8, v70
	s_waitcnt lgkmcnt(0)
	v_add_u32_e32 v4, s16, v70
	v_ashrrev_i32_e32 v5, 31, v4
	v_add_u32_e32 v8, s16, v71
	v_and_b32_e32 v67, 63, v0
	v_mul_lo_u32 v6, s44, v5
	v_mul_lo_u32 v7, s45, v4
	v_mad_u64_u32 v[4:5], s[0:1], s44, v4, 0
	v_ashrrev_i32_e32 v9, 31, v8
	v_lshlrev_b32_e32 v3, 2, v67
	v_add3_u32 v5, v5, v6, v7
	s_ashr_i32 s35, s34, 31
	v_mul_lo_u32 v10, s44, v9
	v_mul_lo_u32 v11, s45, v8
	v_mad_u64_u32 v[8:9], s[22:23], s44, v8, 0
	v_and_b32_e32 v2, 28, v3
	v_lshl_add_u64 v[4:5], v[4:5], 2, s[10:11]
	s_lshl_b64 s[0:1], s[34:35], 2
	v_add3_u32 v9, v9, v10, v11
	v_lshl_add_u64 v[4:5], v[4:5], 0, s[0:1]
	v_lshlrev_b32_e32 v6, 2, v2
	v_mov_b32_e32 v7, v1
	v_lshl_add_u64 v[8:9], v[8:9], 2, s[10:11]
	v_or_b32_e32 v72, 16, v70
	v_lshl_add_u64 v[4:5], v[4:5], 0, v[6:7]
	v_lshl_add_u64 v[8:9], v[8:9], 0, s[0:1]
	v_lshl_add_u64 v[8:9], v[8:9], 0, v[6:7]
	global_load_dwordx4 v[58:61], v[4:5], off nt
	global_load_dwordx4 v[42:45], v[8:9], off nt
	v_add_u32_e32 v4, s16, v72
	v_ashrrev_i32_e32 v5, 31, v4
	v_or_b32_e32 v73, 24, v70
	v_mul_lo_u32 v8, s44, v5
	v_mul_lo_u32 v9, s45, v4
	v_mad_u64_u32 v[4:5], s[22:23], s44, v4, 0
	v_add3_u32 v5, v5, v8, v9
	v_add_u32_e32 v8, s16, v73
	v_ashrrev_i32_e32 v9, 31, v8
	v_mul_lo_u32 v10, s44, v9
	v_mul_lo_u32 v11, s45, v8
	v_mad_u64_u32 v[8:9], s[22:23], s44, v8, 0
	v_lshl_add_u64 v[4:5], v[4:5], 2, s[10:11]
	v_add3_u32 v9, v9, v10, v11
	v_lshl_add_u64 v[4:5], v[4:5], 0, s[0:1]
	v_lshl_add_u64 v[8:9], v[8:9], 2, s[10:11]
	v_or_b32_e32 v74, 32, v70
	v_lshl_add_u64 v[4:5], v[4:5], 0, v[6:7]
	v_lshl_add_u64 v[8:9], v[8:9], 0, s[0:1]
	v_lshl_add_u64 v[8:9], v[8:9], 0, v[6:7]
	global_load_dwordx4 v[54:57], v[4:5], off nt
	global_load_dwordx4 v[38:41], v[8:9], off nt
	v_add_u32_e32 v4, s16, v74
	v_ashrrev_i32_e32 v5, 31, v4
	v_or_b32_e32 v75, 40, v70
	v_mul_lo_u32 v8, s44, v5
	v_mul_lo_u32 v9, s45, v4
	v_mad_u64_u32 v[4:5], s[22:23], s44, v4, 0
	v_add3_u32 v5, v5, v8, v9
	v_add_u32_e32 v8, s16, v75
	v_ashrrev_i32_e32 v9, 31, v8
	v_mul_lo_u32 v10, s44, v9
	v_mul_lo_u32 v11, s45, v8
	v_mad_u64_u32 v[8:9], s[22:23], s44, v8, 0
	v_lshl_add_u64 v[4:5], v[4:5], 2, s[10:11]
	v_add3_u32 v9, v9, v10, v11
	v_lshl_add_u64 v[4:5], v[4:5], 0, s[0:1]
	v_lshl_add_u64 v[8:9], v[8:9], 2, s[10:11]
	v_or_b32_e32 v76, 48, v70
	v_lshl_add_u64 v[4:5], v[4:5], 0, v[6:7]
	v_lshl_add_u64 v[8:9], v[8:9], 0, s[0:1]
	v_lshl_add_u64 v[8:9], v[8:9], 0, v[6:7]
	global_load_dwordx4 v[50:53], v[4:5], off nt
	global_load_dwordx4 v[34:37], v[8:9], off nt
	v_add_u32_e32 v4, s16, v76
	v_ashrrev_i32_e32 v5, 31, v4
	v_or_b32_e32 v77, 56, v70
	v_mul_lo_u32 v8, s44, v5
	v_mul_lo_u32 v9, s45, v4
	v_mad_u64_u32 v[4:5], s[22:23], s44, v4, 0
	v_add3_u32 v5, v5, v8, v9
	v_add_u32_e32 v8, s16, v77
	v_ashrrev_i32_e32 v9, 31, v8
	v_mul_lo_u32 v10, s44, v9
	v_mul_lo_u32 v11, s45, v8
	v_mad_u64_u32 v[8:9], s[22:23], s44, v8, 0
	v_lshl_add_u64 v[4:5], v[4:5], 2, s[10:11]
	v_add3_u32 v9, v9, v10, v11
	v_lshl_add_u64 v[4:5], v[4:5], 0, s[0:1]
	v_lshl_add_u64 v[8:9], v[8:9], 2, s[10:11]
	v_lshl_add_u64 v[4:5], v[4:5], 0, v[6:7]
	v_lshl_add_u64 v[8:9], v[8:9], 0, s[0:1]
	v_lshl_add_u64 v[8:9], v[8:9], 0, v[6:7]
	global_load_dwordx4 v[46:49], v[4:5], off nt
	global_load_dwordx4 v[62:65], v[8:9], off nt
	v_readlane_b32 s0, v250, 6
	v_mul_u32_u24_e32 v4, 0x90, v70
	s_movk_i32 s1, 0x90
	v_add_u32_e32 v86, s0, v3
	v_lshlrev_b32_e32 v3, 3, v0
	v_add3_u32 v78, s0, v4, v6
	v_and_b32_e32 v4, 56, v3
	v_mov_b32_e32 v3, s0
	v_and_b32_e32 v66, 31, v0
	v_mad_u32_u24 v3, v4, s1, v3
	v_lshlrev_b32_e32 v5, 1, v4
	v_lshlrev_b32_e32 v6, 2, v70
	v_bfe_u32 v0, v0, 5, 1
	v_readlane_b32 s1, v254, 5
	v_add3_u32 v88, v3, v5, v6
	v_lshlrev_b32_e32 v3, 2, v66
	v_lshl_add_u32 v89, v0, 7, s1
	v_mul_u32_u24_e32 v0, 0x1240, v0
	v_add_u32_e32 v79, 0x480, v78
	v_add_u32_e32 v80, 0x900, v78
	v_add_u32_e32 v81, 0xd80, v78
	v_add_u32_e32 v82, 0x1200, v78
	v_add_u32_e32 v83, 0x1680, v78
	v_add_u32_e32 v84, 0x1b00, v78
	v_add_u32_e32 v85, 0x1f80, v78
	v_cmp_gt_u32_e64 s[10:11], 32, v67
	v_lshl_add_u32 v87, v4, 2, s0
	v_add3_u32 v90, v0, v3, s0
	v_lshlrev_b32_e32 v68, 2, v2
	v_lshlrev_b32_e32 v0, 1, v4
	s_mov_b32 s2, s40
	s_mov_b64 s[24:25], s[64:65]
	s_mov_b64 s[26:27], s[84:85]
	s_mov_b64 s[22:23], s[14:15]
	s_mov_b64 s[60:61], s[20:21]
	s_mov_b64 s[30:31], s[18:19]
	s_branch .LBB0_1567
